# rw_post: ln_w/ln_b slices of all four column tiles fetched together at the first tile (copied into place later)
# baseline (speedup 1.0000x reference)
; __device__ __forceinline__ f32x4 unpk4(u32x2 w) { return (f32x4){__uint_as_float(w.x << 16), __uint_as_float(w.x & 0xffff0000u), __uint_as_float(w.y << 16), __uint_as_float(w.y & 0xffff0000u)}; }
; __device__ __forceinline__ f32x4 sigm4(f32x4 x) { return (f32x4){sigm(x[0]), sigm(x[1]), sigm(x[2]), sigm(x[3])}; }
; __device__ __forceinline__ u32x2 pk4(f32x4 x) { u32x2 w; w.x = cvt_pk_bf16(x[0], x[1]); w.y = cvt_pk_bf16(x[2], x[3]); return w; }
; __device__ __forceinline__ void rw_post(const bf16_t* Vg, const bf16_t* VF, const bf16_t* LO, const bf16_t* gbT, const bf16_t* vlbT, const float* v0, const bf16_t* WKV, const float* BON, const float* ln_w, const float* ln_b, bf16_t* Y, bf16_t* VFout) {
;     ...
;         const float rstd = rsqrtf(vs * (1.f / 64.f) + 64e-5f);
; #pragma unroll
;         for (int td = 0; td < 4; ++td) { f32x4 v4 = unpk4(vv[td]);
;             if (hasvf) { const f32x4 vf4 = unpk4(vf[td]); v4 = v4 + (vf4 - v4) * sigm4(*(const f32x4*)(v0 + cb + td * 16) + accv[td]); }
;             else *(u32x2*)(VFout + row * 1024 + cb + td * 16) = vv[td];
;             const f32x4 y = ((wk[td] - mean) * rstd * *(const f32x4*)(ln_w + cb + td * 16) + *(const f32x4*)(ln_b + cb + td * 16) + v4 * bon) * acc[td];
;             *(u32x2*)(Y + row * 1024 + cb + td * 16) = pk4(y); }
.LBB0_353:
	v_mov_b32_e32 v2, v144
	v_mov_b32_e32 v3, v144
	v_pk_mul_f32 v[2:3], v[132:133], v[2:3]
	v_pk_mul_f32 v[116:117], v[134:135], v[144:145]
	s_add_i32 s38, s38, s96
	s_cmpk_gt_i32 s38, 0xfff
	s_waitcnt vmcnt(0)
	v_mov_b32_e32 v104, v230
	v_mov_b32_e32 v105, v231
	v_mov_b32_e32 v106, v232
	v_mov_b32_e32 v107, v233
	v_mov_b32_e32 v112, v234
	v_mov_b32_e32 v113, v235
	v_mov_b32_e32 v114, v236
	v_mov_b32_e32 v115, v237
	v_pk_fma_f32 v[2:3], v[2:3], v[106:107], v[114:115]
	v_pk_fma_f32 v[104:105], v[116:117], v[104:105], v[112:113]
	v_mov_b32_e32 v106, v128
	v_mov_b32_e32 v107, v128
	v_pk_fma_f32 v[2:3], v[106:107], v[110:111], v[2:3]
	v_pk_fma_f32 v[104:105], v[128:129], v[108:109], v[104:105]
	v_pk_mul_f32 v[2:3], v[102:103], v[2:3]
	v_pk_mul_f32 v[100:101], v[100:101], v[104:105]
	s_nop 0
	v_cvt_pk_bf16_f32 v100, v100, v101
	v_cvt_pk_bf16_f32 v101, v2, v3
	global_store_dwordx2 v[130:131], v[100:101], off offset:96
	s_cbranch_scc1 .LBB0_399

; __device__ __forceinline__ f32x4 unpk4(u32x2 w) { return (f32x4){__uint_as_float(w.x << 16), __uint_as_float(w.x & 0xffff0000u), __uint_as_float(w.y << 16), __uint_as_float(w.y & 0xffff0000u)}; }
; __device__ __forceinline__ f32x4 sigm4(f32x4 x) { return (f32x4){sigm(x[0]), sigm(x[1]), sigm(x[2]), sigm(x[3])}; }
; __device__ __forceinline__ u32x2 pk4(f32x4 x) { u32x2 w; w.x = cvt_pk_bf16(x[0], x[1]); w.y = cvt_pk_bf16(x[2], x[3]); return w; }
; __device__ __forceinline__ void rw_post(const bf16_t* Vg, const bf16_t* VF, const bf16_t* LO, const bf16_t* gbT, const bf16_t* vlbT, const float* v0, const bf16_t* WKV, const float* BON, const float* ln_w, const float* ln_b, bf16_t* Y, bf16_t* VFout) {
;     ...
;         const float rstd = rsqrtf(vs * (1.f / 64.f) + 64e-5f);
; #pragma unroll
;         for (int td = 0; td < 4; ++td) { f32x4 v4 = unpk4(vv[td]);
;             if (hasvf) { const f32x4 vf4 = unpk4(vf[td]); v4 = v4 + (vf4 - v4) * sigm4(*(const f32x4*)(v0 + cb + td * 16) + accv[td]); }
;             else *(u32x2*)(VFout + row * 1024 + cb + td * 16) = vv[td];
;             const f32x4 y = ((wk[td] - mean) * rstd * *(const f32x4*)(ln_w + cb + td * 16) + *(const f32x4*)(ln_b + cb + td * 16) + v4 * bon) * acc[td];
;             *(u32x2*)(Y + row * 1024 + cb + td * 16) = pk4(y); }
.LBB0_387:
	v_readlane_b32 s2, v251, 26
	v_readlane_b32 s3, v251, 27
	v_mov_b32_e32 v173, v0
	v_add_f32_e32 v128, v228, v229
	v_lshl_add_u64 v[130:131], s[2:3], 0, v[180:181]
	v_lshl_add_u64 v[130:131], v[130:131], 0, v[172:173]
	global_load_dwordx4 v[172:175], v150, s[20:21]
	global_load_dwordx4 v[180:183], v150, s[22:23]
	global_load_dwordx4 v[202:205], v150, s[20:21] offset:64
	global_load_dwordx4 v[206:209], v150, s[22:23] offset:64
	global_load_dwordx4 v[210:213], v150, s[20:21] offset:128
	global_load_dwordx4 v[214:217], v150, s[22:23] offset:128
	global_load_dwordx4 v[230:233], v150, s[20:21] offset:192
	global_load_dwordx4 v[234:237], v150, s[22:23] offset:192
	v_add_f32_e32 v1, v1, v227
	v_add_f32_e32 v128, v1, v128
	s_waitcnt lgkmcnt(0)
	v_add_f32_e32 v1, v144, v145
	v_mov_b32_e32 v129, 0x3a27c5ac
	v_fmamk_f32 v1, v1, 0x3c800000, v129
	v_cmp_gt_f32_e32 vcc, s1, v1
	v_mul_f32_e32 v129, 0x4b800000, v1
	s_mov_b64 s[26:27], -1
	v_cndmask_b32_e32 v1, v1, v129, vcc
	v_rsq_f32_e32 v1, v1
	s_nop 0
	v_mul_f32_e32 v129, 0x45800000, v1
	v_cndmask_b32_e32 v144, v1, v129, vcc
	v_pk_mul_f32 v[184:185], v[192:193], v[144:145] op_sel_hi:[1,0]
	v_pk_mul_f32 v[186:187], v[190:191], v[144:145] op_sel_hi:[1,0]
	s_and_b64 vcc, exec, s[68:69]
	s_waitcnt vmcnt(0)
	v_pk_fma_f32 v[174:175], v[186:187], v[174:175], v[182:183]
	v_pk_fma_f32 v[172:173], v[184:185], v[172:173], v[180:181]
	v_pk_fma_f32 v[174:175], v[128:129], v[176:177], v[174:175] op_sel_hi:[0,1,1]
	v_pk_fma_f32 v[172:173], v[128:129], v[178:179], v[172:173] op_sel_hi:[0,1,1]
	v_pk_mul_f32 v[126:127], v[126:127], v[174:175]
	v_pk_mul_f32 v[124:125], v[124:125], v[172:173]
	s_nop 0
	v_cvt_pk_bf16_f32 v124, v124, v125
	v_cvt_pk_bf16_f32 v125, v126, v127
	global_store_dwordx2 v[130:131], v[124:125], off
	s_cbranch_vccz .LBB0_389
	global_store_dwordx2 v[136:137], v[170:171], off offset:32
	s_mov_b64 s[26:27], 0

; __device__ __forceinline__ u32x2 pk4(f32x4 x) { u32x2 w; w.x = cvt_pk_bf16(x[0], x[1]); w.y = cvt_pk_bf16(x[2], x[3]); return w; }
; __device__ __forceinline__ void rw_post(const bf16_t* Vg, const bf16_t* VF, const bf16_t* LO, const bf16_t* gbT, const bf16_t* vlbT, const float* v0, const bf16_t* WKV, const float* BON, const float* ln_w, const float* ln_b, bf16_t* Y, bf16_t* VFout) {
;     ...
;             else *(u32x2*)(VFout + row * 1024 + cb + td * 16) = vv[td];
;             const f32x4 y = ((wk[td] - mean) * rstd * *(const f32x4*)(ln_w + cb + td * 16) + *(const f32x4*)(ln_b + cb + td * 16) + v4 * bon) * acc[td];
;             *(u32x2*)(Y + row * 1024 + cb + td * 16) = pk4(y); }
.LBB0_391:
	v_mov_b32_e32 v151, v0
	v_mov_b32_e32 v145, v144
	v_lshl_add_u64 v[120:121], s[20:21], 0, v[150:151]
	v_lshl_add_u64 v[122:123], s[22:23], 0, v[150:151]
	v_mov_b32_e32 v150, v144
	v_mov_b32_e32 v151, v144
	v_pk_mul_f32 v[150:151], v[146:147], v[150:151]
	v_pk_mul_f32 v[172:173], v[148:149], v[144:145]
	v_mov_b32_e32 v129, v128
	s_mov_b64 s[26:27], -1
	s_and_b64 vcc, exec, s[68:69]
	s_waitcnt vmcnt(0)
	v_mov_b32_e32 v146, v202
	v_mov_b32_e32 v147, v203
	v_mov_b32_e32 v148, v204
	v_mov_b32_e32 v149, v205
	v_mov_b32_e32 v168, v206
	v_mov_b32_e32 v169, v207
	v_mov_b32_e32 v170, v208
	v_mov_b32_e32 v171, v209
	v_pk_fma_f32 v[148:149], v[150:151], v[148:149], v[170:171]
	v_pk_fma_f32 v[146:147], v[172:173], v[146:147], v[168:169]
	v_mov_b32_e32 v150, v128
	v_mov_b32_e32 v151, v128
	v_pk_fma_f32 v[126:127], v[150:151], v[126:127], v[148:149]
	v_pk_fma_f32 v[124:125], v[128:129], v[124:125], v[146:147]
	v_pk_mul_f32 v[118:119], v[118:119], v[126:127]
	v_pk_mul_f32 v[116:117], v[116:117], v[124:125]
	s_nop 0
	v_cvt_pk_bf16_f32 v116, v116, v117
	v_cvt_pk_bf16_f32 v117, v118, v119
	global_store_dwordx2 v[130:131], v[116:117], off offset:32
	s_cbranch_vccz .LBB0_393
	global_store_dwordx2 v[136:137], v[166:167], off offset:64
	s_mov_b64 s[26:27], 0

; __device__ __forceinline__ u32x2 pk4(f32x4 x) { u32x2 w; w.x = cvt_pk_bf16(x[0], x[1]); w.y = cvt_pk_bf16(x[2], x[3]); return w; }
; __device__ __forceinline__ void rw_post(const bf16_t* Vg, const bf16_t* VF, const bf16_t* LO, const bf16_t* gbT, const bf16_t* vlbT, const float* v0, const bf16_t* WKV, const float* BON, const float* ln_w, const float* ln_b, bf16_t* Y, bf16_t* VFout) {
;     ...
;             else *(u32x2*)(VFout + row * 1024 + cb + td * 16) = vv[td];
;             const f32x4 y = ((wk[td] - mean) * rstd * *(const f32x4*)(ln_w + cb + td * 16) + *(const f32x4*)(ln_b + cb + td * 16) + v4 * bon) * acc[td];
;             *(u32x2*)(Y + row * 1024 + cb + td * 16) = pk4(y); }
.LBB0_395:
	v_mov_b32_e32 v112, v144
	v_mov_b32_e32 v113, v144
	v_pk_mul_f32 v[138:139], v[138:139], v[112:113]
	v_pk_mul_f32 v[140:141], v[140:141], v[144:145]
	s_mov_b64 s[26:27], -1
	s_and_b64 vcc, exec, s[68:69]
	s_waitcnt vmcnt(0)
	v_mov_b32_e32 v112, v210
	v_mov_b32_e32 v113, v211
	v_mov_b32_e32 v114, v212
	v_mov_b32_e32 v115, v213
	v_mov_b32_e32 v124, v214
	v_mov_b32_e32 v125, v215
	v_mov_b32_e32 v126, v216
	v_mov_b32_e32 v127, v217
	v_pk_fma_f32 v[114:115], v[138:139], v[114:115], v[126:127]
	v_pk_fma_f32 v[112:113], v[140:141], v[112:113], v[124:125]
	v_mov_b32_e32 v124, v128
	v_mov_b32_e32 v125, v128
	v_pk_fma_f32 v[114:115], v[124:125], v[118:119], v[114:115]
	v_pk_fma_f32 v[112:113], v[128:129], v[116:117], v[112:113]
	v_pk_mul_f32 v[110:111], v[110:111], v[114:115]
	v_pk_mul_f32 v[108:109], v[108:109], v[112:113]
	s_nop 0
	v_cvt_pk_bf16_f32 v108, v108, v109
	v_cvt_pk_bf16_f32 v109, v110, v111
	global_store_dwordx2 v[130:131], v[108:109], off offset:64
	s_cbranch_vccz .LBB0_397
	global_store_dwordx2 v[136:137], v[162:163], off offset:96
	s_mov_b64 s[26:27], 0
